# stick-breaking attention: exact early exit of key-tile sweep once all lanes tail-sum >= 192 (exp2(-T) underflows to exactly 0 in f32, remaining weights exactly 0; bit-identical output)
# speedup vs baseline: 1.1535x; 1.1473x over previous
; __device__ __forceinline__ void attn_unit(LAS unsigned char* lds, const int wid, int b, int h, int qb, const bf16_t* __restrict__ Q, const bf16_t* __restrict__ K,
;                                           const bf16_t* __restrict__ V, const bf16_t* __restrict__ ZS, bf16_t* __restrict__ OG) {
;     ...
;     for (int t = NT - 1; t >= 0; --t) {
;         if (t > 0) ATT_STAGE(t - 1, (kcur ^ 1) * 16384, 32768 + vnext * 16384);
;     ...
;         prev_valid = valid;
;         asm volatile("s_waitcnt vmcnt(0)" ::: "memory");
;         __syncthreads();
;         kcur ^= 1; { const int tmp = vprev; vprev = vcur; vcur = vnext; vnext = tmp; }
;     }
.LBB0_609:
	s_waitcnt vmcnt(0)
	s_xor_b32 s67, s67, 1
	s_add_i32 s42, s42, -1
	s_sub_i32 s65, s65, 64
	v_cmp_gt_f32_e32 vcc, 0x43400000, v158
	s_lshr_b32 s98, s54, 3
	s_lshl_b32 s99, s67, 5
	s_add_i32 s98, s98, s99
	s_add_i32 s98, s98, 0x24000
	s_cmp_lg_u64 vcc, 0
	s_cselect_b32 s99, 1, 0
	v_mov_b32_e32 v80, s98
	v_mov_b32_e32 v81, s99
	s_mov_b64 s[100:101], exec
	s_mov_b64 exec, 1
	ds_write_b32 v80, v81
	s_mov_b64 exec, s[100:101]
	s_cmpk_lg_i32 s65, 0xffc0
	s_waitcnt vmcnt(0) lgkmcnt(0)
	s_barrier
	s_cbranch_scc0 .LBB0_611
	s_lshl_b32 s98, s67, 5
	s_add_i32 s98, s98, 0x24000
	v_mov_b32_e32 v80, s98
	ds_read_b128 v[84:87], v80
	ds_read_b128 v[88:91], v80 offset:16
	s_waitcnt lgkmcnt(0)
	v_or3_b32 v84, v84, v85, v86
	v_or3_b32 v88, v88, v89, v90
	v_or3_b32 v84, v84, v87, v91
	v_or_b32_e32 v84, v84, v88
	s_nop 0
	v_readfirstlane_b32 s99, v84
	s_cmp_eq_u32 s99, 0
	s_cbranch_scc1 .LBB0_611
	s_mov_b32 s6, s71
	s_mov_b32 s71, s72
	s_mov_b32 s72, s73
	s_mov_b64 s[4:5], s[52:53]
	s_mov_b32 s73, s6
	s_cmp_lg_u32 s65, 0
	s_mov_b64 s[6:7], -1
	s_cbranch_scc1 .LBB0_595
	s_branch .LBB0_596

; __device__ __forceinline__ void attn_unit(LAS unsigned char* lds, const int wid, int b, int h, int qb, const bf16_t* __restrict__ Q, const bf16_t* __restrict__ K,
;                                           const bf16_t* __restrict__ V, const bf16_t* __restrict__ ZS, bf16_t* __restrict__ OG) {
;     ...
;     for (int t = NT - 1; t >= 0; --t) {
;         if (t > 0) ATT_STAGE(t - 1, (kcur ^ 1) * 16384, 32768 + vnext * 16384);
;     ...
;         prev_valid = valid;
;         asm volatile("s_waitcnt vmcnt(0)" ::: "memory");
;         __syncthreads();
;         kcur ^= 1; { const int tmp = vprev; vprev = vcur; vcur = vnext; vnext = tmp; }
;     }
.LBB0_626:
	s_waitcnt vmcnt(0)
	s_xor_b32 s67, s67, 1
	s_add_i32 s42, s42, -1
	s_sub_i32 s66, s66, 64
	v_cmp_gt_f32_e32 vcc, 0x43400000, v158
	s_lshr_b32 s98, s54, 3
	s_lshl_b32 s99, s67, 5
	s_add_i32 s98, s98, s99
	s_add_i32 s98, s98, 0x24000
	s_cmp_lg_u64 vcc, 0
	s_cselect_b32 s99, 1, 0
	v_mov_b32_e32 v80, s98
	v_mov_b32_e32 v81, s99
	s_mov_b64 s[100:101], exec
	s_mov_b64 exec, 1
	ds_write_b32 v80, v81
	s_mov_b64 exec, s[100:101]
	s_cmp_lg_u32 s42, -2
	s_waitcnt vmcnt(0) lgkmcnt(0)
	s_barrier
	s_cbranch_scc0 .LBB0_593
	s_lshl_b32 s98, s67, 5
	s_add_i32 s98, s98, 0x24000
	v_mov_b32_e32 v80, s98
	ds_read_b128 v[84:87], v80
	ds_read_b128 v[88:91], v80 offset:16
	s_waitcnt lgkmcnt(0)
	v_or3_b32 v84, v84, v85, v86
	v_or3_b32 v88, v88, v89, v90
	v_or3_b32 v84, v84, v87, v91
	v_or_b32_e32 v84, v84, v88
	s_nop 0
	v_readfirstlane_b32 s99, v84
	s_cmp_eq_u32 s99, 0
	s_cbranch_scc1 .LBB0_593
	s_mov_b32 s6, s71
	s_mov_b32 s71, s64
	s_mov_b32 s64, s72
	s_mov_b64 s[4:5], s[52:53]
	s_mov_b32 s72, s6
	s_cmp_lg_u32 s42, -1
	s_mov_b64 s[6:7], -1
	s_cbranch_scc1 .LBB0_612
	s_branch .LBB0_613

; __global__ void __launch_bounds__(NWAVES * 64, 2) fwd_kernel(Args a) {
	.amdhsa_kernel _Z10fwd_kernel4Args
		.amdhsa_group_segment_fixed_size 0
		.amdhsa_private_segment_fixed_size 0
		.amdhsa_kernarg_size 368
		.amdhsa_user_sgpr_count 2
		.amdhsa_user_sgpr_dispatch_ptr 0
		.amdhsa_user_sgpr_queue_ptr 0
		.amdhsa_user_sgpr_kernarg_segment_ptr 1
		.amdhsa_user_sgpr_dispatch_id 0
		.amdhsa_user_sgpr_kernarg_preload_length 0
		.amdhsa_user_sgpr_kernarg_preload_offset 0
		.amdhsa_user_sgpr_private_segment_size 0
		.amdhsa_uses_dynamic_stack 0
		.amdhsa_enable_private_segment 0
		.amdhsa_system_sgpr_workgroup_id_x 1
		.amdhsa_system_sgpr_workgroup_id_y 0
		.amdhsa_system_sgpr_workgroup_id_z 0
		.amdhsa_system_sgpr_workgroup_info 0
		.amdhsa_system_vgpr_workitem_id 2
		.amdhsa_next_free_vgpr 249
		.amdhsa_next_free_sgpr 102
		.amdhsa_accum_offset 252
		.amdhsa_reserve_vcc 1
		.amdhsa_float_round_mode_32 0
		.amdhsa_float_round_mode_16_64 0
		.amdhsa_float_denorm_mode_32 3
		.amdhsa_float_denorm_mode_16_64 3
		.amdhsa_dx10_clamp 1
		.amdhsa_ieee_mode 1
		.amdhsa_fp16_overflow 0
		.amdhsa_tg_split 0
		.amdhsa_exception_fp_ieee_invalid_op 0
		.amdhsa_exception_fp_denorm_src 0
		.amdhsa_exception_fp_ieee_div_zero 0
		.amdhsa_exception_fp_ieee_overflow 0
		.amdhsa_exception_fp_ieee_underflow 0
		.amdhsa_exception_fp_ieee_inexact 0
		.amdhsa_exception_int_div_zero 0
	.end_amdhsa_kernel

; __global__ void __launch_bounds__(NWAVES * 64, 2) fwd_kernel(Args a) {
amdhsa.kernels:
  - .agpr_count:     0
    .args:
      - .offset:         0
        .size:           112
        .value_kind:     by_value
      - .offset:         112
        .size:           4
        .value_kind:     hidden_block_count_x
      - .offset:         116
        .size:           4
        .value_kind:     hidden_block_count_y
      - .offset:         120
        .size:           4
        .value_kind:     hidden_block_count_z
      - .offset:         124
        .size:           2
        .value_kind:     hidden_group_size_x
      - .offset:         126
        .size:           2
        .value_kind:     hidden_group_size_y
      - .offset:         128
        .size:           2
        .value_kind:     hidden_group_size_z
      - .offset:         130
        .size:           2
        .value_kind:     hidden_remainder_x
      - .offset:         132
        .size:           2
        .value_kind:     hidden_remainder_y
      - .offset:         134
        .size:           2
        .value_kind:     hidden_remainder_z
      - .offset:         152
        .size:           8
        .value_kind:     hidden_global_offset_x
      - .offset:         160
        .size:           8
        .value_kind:     hidden_global_offset_y
      - .offset:         168
        .size:           8
        .value_kind:     hidden_global_offset_z
      - .offset:         176
        .size:           2
        .value_kind:     hidden_grid_dims
      - .offset:         200
        .size:           8
        .value_kind:     hidden_multigrid_sync_arg
      - .offset:         232
        .size:           4
        .value_kind:     hidden_dynamic_lds_size
    .group_segment_fixed_size: 0
    .kernarg_segment_align: 8
    .kernarg_segment_size: 368
    .language:       OpenCL C
    .language_version:
      - 2
      - 0
    .max_flat_workgroup_size: 512
    .name:           _Z10fwd_kernel4Args
    .private_segment_fixed_size: 0
    .sgpr_count:     108
    .sgpr_spill_count: 60
    .symbol:         _Z10fwd_kernel4Args.kd
    .uniform_work_group_size: 1
    .uses_dynamic_stack: false
    .vgpr_count:     249
    .vgpr_spill_count: 0
    .wavefront_size: 64
